# attention tile loop: 8 K-fragment LDS reads batched, V-fragment reads hoisted above the softmax / issued behind the MFMAs that free their registers
# baseline (speedup 1.0000x reference)
.LBB0_873:
	s_cmpk_eq_i32 s71, 0xffd0
	s_cselect_b64 s[34:35], -1, 0
	s_and_b64 s[4:5], s[34:35], exec
	s_cselect_b32 s84, 0, s71
	s_cmp_gt_i32 s84, s29
	s_cselect_b64 s[4:5], -1, 0
	s_or_b64 s[4:5], s[58:59], s[4:5]
	s_and_b64 vcc, exec, s[4:5]
	s_cbranch_vccnz .LBB0_883
	ds_read_b128 v[88:91], v221
	ds_read_b128 v[92:95], v221 offset:64
	ds_read_b128 v[164:167], v221 offset:576
	ds_read_b128 v[168:171], v221 offset:640
	ds_read_b128 v[172:175], v221 offset:4608
	ds_read_b128 v[236:239], v221 offset:4672
	ds_read_b128 v[240:243], v221 offset:5184
	ds_read_b128 v[160:163], v221 offset:5248
	s_add_i32 s4, s84, 63
	s_cmp_gt_i32 s4, s95
	s_cselect_b64 s[4:5], -1, 0
	s_or_b64 s[74:75], s[34:35], s[4:5]
	s_cmpk_lg_i32 s71, 0xffd0
	s_mov_b64 s[34:35], -1
	s_cselect_b64 s[72:73], -1, 0
	s_and_b64 vcc, exec, s[74:75]
	s_waitcnt lgkmcnt(6)
	v_mfma_f32_16x16x32_bf16 v[96:99], v[88:91], v[0:3], 0
	v_mfma_f32_16x16x32_bf16 v[88:91], v[88:91], v[8:11], 0
	v_mfma_f32_16x16x32_bf16 v[116:119], v[92:95], v[4:7], v[96:99]
	v_mfma_f32_16x16x32_bf16 v[100:103], v[92:95], v[12:15], v[88:91]
	s_waitcnt lgkmcnt(4)
	s_nop 1
	v_mfma_f32_16x16x32_bf16 v[96:99], v[164:167], v[0:3], 0
	v_mfma_f32_16x16x32_bf16 v[88:91], v[164:167], v[8:11], 0
	v_mfma_f32_16x16x32_bf16 v[112:115], v[168:171], v[4:7], v[96:99]
	v_mfma_f32_16x16x32_bf16 v[96:99], v[168:171], v[12:15], v[88:91]
	s_waitcnt lgkmcnt(2)
	s_nop 1
	v_mfma_f32_16x16x32_bf16 v[104:107], v[172:175], v[0:3], 0
	v_mfma_f32_16x16x32_bf16 v[88:91], v[172:175], v[8:11], 0
	v_mfma_f32_16x16x32_bf16 v[108:111], v[236:239], v[4:7], v[104:107]
	v_mfma_f32_16x16x32_bf16 v[92:95], v[236:239], v[12:15], v[88:91]
	s_waitcnt lgkmcnt(0)
	s_nop 1
	v_mfma_f32_16x16x32_bf16 v[104:107], v[240:243], v[0:3], 0
	v_mfma_f32_16x16x32_bf16 v[88:91], v[240:243], v[8:11], 0
	v_mfma_f32_16x16x32_bf16 v[104:107], v[160:163], v[4:7], v[104:107]
	v_mfma_f32_16x16x32_bf16 v[88:91], v[160:163], v[12:15], v[88:91]
	ds_read_b128 v[236:239], v222 offset:9216
	ds_read_b128 v[240:243], v222 offset:9280
	ds_read_b128 v[244:247], v222 offset:11520
	ds_read_b128 v[248:251], v222 offset:11584
	s_cbranch_vccnz .LBB0_876
	v_pk_add_f32 v[160:161], v[140:141], v[84:85] neg_lo:[0,1] neg_hi:[0,1]
	v_pk_add_f32 v[162:163], v[140:141], v[86:87] neg_lo:[0,1] neg_hi:[0,1]
	v_pk_add_f32 v[160:161], v[160:161], v[116:117]
	v_pk_add_f32 v[162:163], v[162:163], v[118:119]
	v_max3_f32 v164, v160, s86, v161
	v_max3_f32 v166, v164, v162, v163
	v_pk_add_f32 v[164:165], v[140:141], v[76:77] neg_lo:[0,1] neg_hi:[0,1]
	s_mov_b64 s[34:35], 0
	v_pk_add_f32 v[164:165], v[164:165], v[112:113]
	s_nop 0
	v_max3_f32 v170, v166, v164, v165
	v_pk_add_f32 v[166:167], v[140:141], v[78:79] neg_lo:[0,1] neg_hi:[0,1]
	s_nop 0
	v_pk_add_f32 v[168:169], v[166:167], v[114:115]
	v_pk_add_f32 v[166:167], v[140:141], v[80:81] neg_lo:[0,1] neg_hi:[0,1]
	v_max3_f32 v170, v170, v168, v169
	v_pk_add_f32 v[166:167], v[166:167], v[108:109]
	s_nop 0
	v_max3_f32 v172, v170, v166, v167
	v_pk_add_f32 v[170:171], v[140:141], v[82:83] neg_lo:[0,1] neg_hi:[0,1]
	s_nop 0
	v_pk_add_f32 v[170:171], v[170:171], v[110:111]
	s_nop 0
	v_max3_f32 v174, v172, v170, v171
	v_pk_add_f32 v[172:173], v[140:141], v[72:73] neg_lo:[0,1] neg_hi:[0,1]
	s_nop 0
	v_pk_add_f32 v[172:173], v[172:173], v[104:105]
	s_nop 0
	v_max3_f32 v202, v174, v172, v173
	v_pk_add_f32 v[174:175], v[140:141], v[74:75] neg_lo:[0,1] neg_hi:[0,1]
	s_nop 0
	v_pk_add_f32 v[174:175], v[174:175], v[106:107]
	s_nop 0
	v_max3_f32 v230, v202, v174, v175

.LBB0_882:
	s_waitcnt lgkmcnt(0)
	v_max3_f32 v89, v227, v231, v232
	v_sub_f32_e32 v72, v227, v89
	v_exp_f32_e32 v88, v72
	v_sub_f32_e32 v72, v160, v89
	v_exp_f32_e32 v72, v72
	v_sub_f32_e32 v74, v161, v89
	v_exp_f32_e32 v74, v74
	v_sub_f32_e32 v75, v162, v89
	v_sub_f32_e32 v76, v163, v89
	v_exp_f32_e32 v75, v75
	v_exp_f32_e32 v77, v76
	v_sub_f32_e32 v76, v164, v89
	v_exp_f32_e32 v78, v76
	v_sub_f32_e32 v76, v165, v89
	v_add_f32_e32 v73, 0, v72
	v_exp_f32_e32 v79, v76
	v_sub_f32_e32 v76, v168, v89
	v_add_f32_e32 v73, v74, v73
	v_exp_f32_e32 v80, v76
	v_sub_f32_e32 v76, v169, v89
	v_add_f32_e32 v73, v75, v73
	v_exp_f32_e32 v81, v76
	v_add_f32_e32 v73, v77, v73
	v_cvt_pk_bf16_f32 v76, v72, v74
	v_sub_f32_e32 v72, v166, v89
	v_add_f32_e32 v73, v78, v73
	v_exp_f32_e32 v72, v72
	v_sub_f32_e32 v74, v167, v89
	v_add_f32_e32 v73, v79, v73
	v_cvt_pk_bf16_f32 v77, v75, v77
	v_exp_f32_e32 v74, v74
	v_sub_f32_e32 v75, v170, v89
	v_add_f32_e32 v73, v80, v73
	v_cvt_pk_bf16_f32 v78, v78, v79
	v_cvt_pk_bf16_f32 v79, v80, v81
	v_exp_f32_e32 v75, v75
	v_sub_f32_e32 v80, v171, v89
	v_add_f32_e32 v73, v81, v73
	v_exp_f32_e32 v80, v80
	v_sub_f32_e32 v81, v172, v89
	v_add_f32_e32 v73, v72, v73
	v_exp_f32_e32 v81, v81
	v_sub_f32_e32 v82, v173, v89
	v_add_f32_e32 v73, v74, v73
	v_exp_f32_e32 v82, v82
	v_sub_f32_e32 v83, v174, v89
	v_add_f32_e32 v73, v75, v73
	v_exp_f32_e32 v83, v83
	v_sub_f32_e32 v84, v175, v89
	v_add_f32_e32 v73, v80, v73
	v_exp_f32_e32 v84, v84
	v_add_f32_e32 v73, v81, v73
	v_add_f32_e32 v73, v82, v73
	v_add_f32_e32 v73, v83, v73
	v_add_f32_e32 v91, v84, v73
	v_cvt_pk_bf16_f32 v73, v75, v80
	ds_bpermute_b32 v80, v229, v230
	v_cvt_pk_bf16_f32 v72, v72, v74
	v_cvt_pk_bf16_f32 v74, v81, v82
	v_max_f32_e32 v81, v230, v230
	v_cvt_pk_bf16_f32 v75, v83, v84
	s_waitcnt lgkmcnt(0)
	v_max_f32_e32 v80, v80, v80
	v_max_f32_e32 v80, v81, v80
	ds_bpermute_b32 v81, v228, v80
	v_fmac_f32_e32 v91, v225, v88
	v_pk_mul_f32 v[54:55], v[54:55], v[88:89] op_sel_hi:[1,0]
	v_pk_mul_f32 v[52:53], v[52:53], v[88:89] op_sel_hi:[1,0]
	v_pk_mul_f32 v[46:47], v[46:47], v[88:89] op_sel_hi:[1,0]
	s_waitcnt lgkmcnt(0)
	v_max3_f32 v92, v226, v80, v81
	v_sub_f32_e32 v80, v226, v92
	v_exp_f32_e32 v90, v80
	v_sub_f32_e32 v80, v104, v92
	v_exp_f32_e32 v80, v80
	v_sub_f32_e32 v82, v105, v92
	v_exp_f32_e32 v82, v82
	v_sub_f32_e32 v83, v106, v92
	v_sub_f32_e32 v84, v107, v92
	v_exp_f32_e32 v83, v83
	v_exp_f32_e32 v85, v84
	v_sub_f32_e32 v84, v108, v92
	v_exp_f32_e32 v86, v84
	v_sub_f32_e32 v84, v109, v92
	v_add_f32_e32 v81, 0, v80
	v_exp_f32_e32 v87, v84
	v_sub_f32_e32 v84, v110, v92
	v_add_f32_e32 v81, v82, v81
	v_exp_f32_e32 v93, v84
	v_sub_f32_e32 v84, v111, v92
	v_add_f32_e32 v81, v83, v81
	v_exp_f32_e32 v94, v84
	v_add_f32_e32 v81, v85, v81
	v_cvt_pk_bf16_f32 v84, v80, v82
	v_sub_f32_e32 v80, v112, v92
	v_add_f32_e32 v81, v86, v81
	v_exp_f32_e32 v80, v80
	v_sub_f32_e32 v82, v113, v92
	v_add_f32_e32 v81, v87, v81
	v_cvt_pk_bf16_f32 v85, v83, v85
	v_exp_f32_e32 v82, v82
	v_sub_f32_e32 v83, v114, v92
	v_add_f32_e32 v81, v93, v81
	v_cvt_pk_bf16_f32 v86, v86, v87
	v_cvt_pk_bf16_f32 v87, v93, v94
	v_exp_f32_e32 v83, v83
	v_sub_f32_e32 v93, v115, v92
	v_add_f32_e32 v81, v94, v81
	v_exp_f32_e32 v94, v93
	v_sub_f32_e32 v93, v116, v92
	v_add_f32_e32 v81, v80, v81
	v_exp_f32_e32 v95, v93
	v_sub_f32_e32 v93, v117, v92
	v_add_f32_e32 v81, v82, v81
	v_exp_f32_e32 v96, v93
	v_sub_f32_e32 v93, v118, v92
	v_add_f32_e32 v81, v83, v81
	v_exp_f32_e32 v97, v93
	v_sub_f32_e32 v93, v119, v92
	v_add_f32_e32 v81, v94, v81
	v_exp_f32_e32 v98, v93
	v_add_f32_e32 v81, v95, v81
	v_add_f32_e32 v81, v96, v81
	v_add_f32_e32 v81, v97, v81
	v_add_f32_e32 v93, v98, v81
	v_cvt_pk_bf16_f32 v80, v80, v82
	v_cvt_pk_bf16_f32 v81, v83, v94
	v_cvt_pk_bf16_f32 v82, v95, v96
	v_cvt_pk_bf16_f32 v83, v97, v98
	v_pk_mul_f32 v[38:39], v[38:39], v[90:91] op_sel_hi:[1,0]
	v_pk_mul_f32 v[36:37], v[36:37], v[90:91] op_sel_hi:[1,0]
	s_waitcnt lgkmcnt(0)
	v_mfma_f32_16x16x32_bf16 v[52:55], v[236:239], v[76:79], v[52:55]
	v_mul_f32_e64 v44, v44, v88
	v_mul_f32_e64 v45, v45, v88
	v_pk_mul_f32 v[30:31], v[30:31], v[90:91] op_sel_hi:[1,0]
	v_pk_mul_f32 v[28:29], v[28:29], v[90:91] op_sel_hi:[1,0]
	v_mfma_f32_16x16x32_bf16 v[36:39], v[236:239], v[84:87], v[36:39]
	ds_read_b128 v[236:239], v222 offset:13824
	v_pk_mul_f32 v[42:43], v[42:43], v[88:89] op_sel_hi:[1,0]
	v_pk_mul_f32 v[40:41], v[40:41], v[88:89] op_sel_hi:[1,0]
	v_mfma_f32_16x16x32_bf16 v[52:55], v[240:243], v[72:75], v[52:55]
	v_mul_f32_e64 v18, v18, v90
	v_mul_f32_e64 v19, v19, v90
	v_pk_mul_f32 v[16:17], v[16:17], v[90:91] op_sel_hi:[1,0]
	v_pk_mul_f32 v[50:51], v[50:51], v[88:89] op_sel_hi:[1,0]
	v_mfma_f32_16x16x32_bf16 v[36:39], v[240:243], v[80:83], v[36:39]
	ds_read_b128 v[240:243], v222 offset:13888
	v_pk_mul_f32 v[48:49], v[48:49], v[88:89] op_sel_hi:[1,0]
	v_pk_mul_f32 v[34:35], v[34:35], v[90:91] op_sel_hi:[1,0]
	v_mfma_f32_16x16x32_bf16 v[44:47], v[244:247], v[76:79], v[44:47]
	v_mul_f32_e64 v32, v32, v90
	v_mul_f32_e64 v33, v33, v90
	v_fmac_f32_e32 v93, v224, v90
	v_mov_b32_e32 v226, v92
	v_mfma_f32_16x16x32_bf16 v[28:31], v[244:247], v[84:87], v[28:31]
	ds_read_b128 v[244:247], v223 offset:9216
	v_mov_b32_e32 v227, v89
	v_mov_b32_e32 v224, v93
	v_mfma_f32_16x16x32_bf16 v[44:47], v[248:251], v[72:75], v[44:47]
	v_mov_b32_e32 v225, v91
	v_mfma_f32_16x16x32_bf16 v[28:31], v[248:251], v[80:83], v[28:31]
	ds_read_b128 v[248:251], v223 offset:9280
	s_waitcnt lgkmcnt(3)
	v_mfma_f32_16x16x32_bf16 v[40:43], v[236:239], v[76:79], v[40:43]
	v_mfma_f32_16x16x32_bf16 v[16:19], v[236:239], v[84:87], v[16:19]
	s_waitcnt lgkmcnt(2)
	v_mfma_f32_16x16x32_bf16 v[40:43], v[240:243], v[72:75], v[40:43]
	v_mfma_f32_16x16x32_bf16 v[16:19], v[240:243], v[80:83], v[16:19]
	s_waitcnt lgkmcnt(1)
	v_mfma_f32_16x16x32_bf16 v[48:51], v[244:247], v[76:79], v[48:51]
	v_mfma_f32_16x16x32_bf16 v[32:35], v[244:247], v[84:87], v[32:35]
	s_waitcnt lgkmcnt(0)
	v_mfma_f32_16x16x32_bf16 v[48:51], v[248:251], v[72:75], v[48:51]
	v_mfma_f32_16x16x32_bf16 v[32:35], v[248:251], v[80:83], v[32:35]
